# P9 epilogue: 4x4 lane-group transpose (permlane16/32 swap) so each f32 output store writes full 64B sectors
# speedup vs baseline: 1.0055x; 1.0055x over previous
.LBB0_1657:
	v_and_b32_e32 v232, 48, v146
	v_mul_u32_u24_e32 v232, 3, v232
	v_sub_u32_e32 v232, 0, v232
	v_ashrrev_i32_e32 v233, 31, v232
	v_lshl_add_u32 v140, s26, 8, v144
	v_ashrrev_i32_e32 v141, 31, v140
	v_lshlrev_b64 v[138:139], 6, v[140:141]
	v_lshl_add_u64 v[138:139], s[6:7], 0, v[138:139]
	global_load_dwordx4 v[152:155], v[138:139], off
	global_load_dwordx4 v[156:159], v[138:139], off offset:16
	global_load_dwordx4 v[160:163], v[138:139], off offset:48
	global_load_dwordx4 v[164:167], v[138:139], off offset:32
	v_lshl_or_b32 v142, s24, 8, v146
	v_ashrrev_i32_e32 v143, 31, v142
	v_lshlrev_b64 v[168:169], 11, v[140:141]
	v_lshlrev_b64 v[138:139], 1, v[142:143]
	v_lshl_add_u64 v[170:171], s[8:9], 0, v[168:169]
	v_lshl_add_u64 v[172:173], s[0:1], 0, v[168:169]
	v_lshl_add_u64 v[176:177], v[170:171], 0, v[138:139]
	v_lshl_add_u64 v[180:181], v[172:173], 0, v[138:139]
	global_load_dwordx4 v[168:171], v[176:177], off
	global_load_dwordx4 v[172:175], v[180:181], off
	s_nop 0
	global_load_dwordx4 v[176:179], v[176:177], off offset:16
	s_nop 0
	global_load_dwordx4 v[180:183], v[180:181], off offset:16
	s_cmp_eq_u32 s25, s47
	s_mov_b64 s[24:25], -1
	s_waitcnt vmcnt(0)
	v_mov_b32_e32 v184, v153
	v_mov_b32_e32 v185, v154
	v_mov_b32_e32 v153, v155
	v_mov_b32_e32 v154, v157
	v_mov_b32_e32 v155, v158
	v_mov_b32_e32 v157, v159
	v_pk_add_f32 v[152:153], v[184:185], v[152:153]
	v_pk_add_f32 v[154:155], v[154:155], v[156:157]
	v_pk_add_f32 v[152:153], v[152:153], v[152:153] op_sel:[0,1] op_sel_hi:[1,0]
	v_pk_add_f32 v[154:155], v[154:155], v[154:155] op_sel:[0,1] op_sel_hi:[1,0]
	v_add_f32_e32 v158, v164, v165
	v_add_f32_e32 v164, v166, v167
	v_mov_b32_e32 v159, v162
	v_mov_b32_e32 v165, v163
	v_mov_b32_e32 v153, v160
	v_mov_b32_e32 v155, v161
	v_pk_add_f32 v[156:157], v[158:159], v[164:165]
	v_pk_add_f32 v[152:153], v[152:153], v[154:155]
	v_lshlrev_b32_e32 v158, 16, v168
	v_pk_add_f32 v[152:153], v[152:153], v[156:157]
	v_and_b32_e32 v159, 0xffff0000, v168
	v_add_f32_e32 v151, v152, v153
	v_fmamk_f32 v151, v151, 0x3a800000, v150
	v_mul_f32_e32 v152, 0x4b800000, v151
	v_cmp_gt_f32_e32 vcc, s51, v151
	v_and_b32_e32 v153, 0xffff0000, v176
	v_lshlrev_b32_e32 v162, 16, v172
	v_cndmask_b32_e32 v151, v151, v152, vcc
	v_rsq_f32_e32 v151, v151
	v_lshlrev_b32_e32 v152, 16, v176
	v_and_b32_e32 v163, 0xffff0000, v172
	v_lshlrev_b32_e32 v164, 16, v169
	v_mul_f32_e32 v155, 0x45800000, v151
	v_cndmask_b32_e32 v151, v151, v155, vcc
	v_mul_f32_e32 v151, 0xbfb8aa3b, v151
	v_mul_f32_e32 v127, v127, v151
	v_mul_f32_e32 v117, v117, v151
	v_mul_f32_e32 v112, v112, v151
	v_mul_f32_e32 v124, v124, v151
	v_mul_f32_e32 v121, v121, v151
	v_mul_f32_e32 v122, v122, v151
	v_exp_f32_e32 v127, v127
	v_exp_f32_e32 v117, v117
	v_exp_f32_e32 v112, v112
	v_mul_f32_e32 v113, v113, v151
	v_mul_f32_e32 v120, v120, v151
	v_mul_f32_e32 v123, v123, v151
	v_exp_f32_e32 v124, v124
	v_exp_f32_e32 v121, v121
	v_exp_f32_e32 v122, v122
	v_exp_f32_e32 v113, v113
	v_exp_f32_e32 v120, v120
	v_exp_f32_e32 v123, v123
	v_add_f32_e32 v127, 1.0, v127
	v_add_f32_e32 v176, 1.0, v117
	v_add_f32_e32 v112, 1.0, v112
	v_mul_f32_e32 v125, v125, v151
	v_mul_f32_e32 v126, v126, v151
	v_add_f32_e32 v124, 1.0, v124
	v_add_f32_e32 v156, 1.0, v121
	v_add_f32_e32 v157, 1.0, v122
	v_rcp_f32_e32 v117, v127
	v_rcp_f32_e32 v127, v176
	v_rcp_f32_e32 v176, v112
	v_add_f32_e32 v112, 1.0, v113
	v_mul_f32_e32 v116, v116, v151
	v_exp_f32_e32 v125, v125
	v_exp_f32_e32 v126, v126
	v_add_f32_e32 v155, 1.0, v120
	v_add_f32_e32 v160, 1.0, v123
	v_rcp_f32_e32 v120, v124
	v_rcp_f32_e32 v123, v156
	v_rcp_f32_e32 v124, v157
	v_lshlrev_b32_e32 v156, 16, v177
	v_and_b32_e32 v157, 0xffff0000, v177
	v_rcp_f32_e32 v177, v112
	v_mul_f32_e32 v112, v114, v151
	v_mul_f32_e32 v118, v118, v151
	v_exp_f32_e32 v116, v116
	v_mul_f32_e32 v119, v119, v151
	v_exp_f32_e32 v112, v112
	v_mul_f32_e32 v113, v115, v151
	v_exp_f32_e32 v118, v118
	v_exp_f32_e32 v119, v119
	v_exp_f32_e32 v113, v113
	v_add_f32_e32 v125, 1.0, v125
	v_add_f32_e32 v126, 1.0, v126
	v_add_f32_e32 v161, 1.0, v116
	v_rcp_f32_e32 v121, v125
	v_rcp_f32_e32 v116, v126
	v_add_f32_e32 v112, 1.0, v112
	v_rcp_f32_e32 v122, v155
	v_rcp_f32_e32 v125, v160
	v_add_f32_e32 v118, 1.0, v118
	v_add_f32_e32 v119, 1.0, v119
	v_rcp_f32_e32 v186, v112
	v_add_f32_e32 v112, 1.0, v113
	v_rcp_f32_e32 v126, v161
	v_rcp_f32_e32 v118, v118
	v_rcp_f32_e32 v119, v119
	v_rcp_f32_e32 v187, v112
	v_lshlrev_b64 v[112:113], 12, v[140:141]
	v_and_b32_e32 v165, 0xffff0000, v169
	v_lshlrev_b32_e32 v166, 16, v173
	v_and_b32_e32 v167, 0xffff0000, v173
	v_lshl_add_u64 v[114:115], s[84:85], 0, v[112:113]
	v_lshlrev_b64 v[112:113], 2, v[142:143]
	v_lshlrev_b32_e32 v168, 16, v170
	v_and_b32_e32 v169, 0xffff0000, v170
	v_lshlrev_b32_e32 v172, 16, v174
	v_and_b32_e32 v173, 0xffff0000, v174
	v_lshlrev_b32_e32 v170, 16, v171
	v_and_b32_e32 v171, 0xffff0000, v171
	v_lshlrev_b32_e32 v174, 16, v175
	v_and_b32_e32 v175, 0xffff0000, v175
	v_lshl_add_u64 v[142:143], v[114:115], 0, v[112:113]
	v_pk_fma_f32 v[218:219], v[116:117], v[164:165], v[166:167]
	v_pk_fma_f32 v[216:217], v[120:121], v[158:159], v[162:163]
	v_lshlrev_b32_e32 v154, 16, v180
	v_and_b32_e32 v155, 0xffff0000, v180
	v_lshlrev_b32_e32 v160, 16, v181
	v_and_b32_e32 v161, 0xffff0000, v181
	v_lshlrev_b32_e32 v180, 16, v178
	v_and_b32_e32 v181, 0xffff0000, v178
	v_pk_fma_f32 v[222:223], v[124:125], v[170:171], v[174:175]
	v_pk_fma_f32 v[220:221], v[122:123], v[168:169], v[172:173]
	v_lshlrev_b32_e32 v184, 16, v182
	v_and_b32_e32 v185, 0xffff0000, v182
	v_lshlrev_b32_e32 v178, 16, v179
	v_and_b32_e32 v179, 0xffff0000, v179
	v_lshlrev_b32_e32 v182, 16, v183
	v_and_b32_e32 v183, 0xffff0000, v183
	s_nop 1
	v_pk_fma_f32 v[226:227], v[118:119], v[156:157], v[160:161]
	v_pk_fma_f32 v[224:225], v[126:127], v[152:153], v[154:155]
	v_or_b32_e32 v126, 16, v140
	v_ashrrev_i32_e32 v127, 31, v126
	s_nop 0
	v_pk_fma_f32 v[230:231], v[186:187], v[178:179], v[182:183]
	v_pk_fma_f32 v[228:229], v[176:177], v[180:181], v[184:185]
	s_nop 1
	v_permlane16_swap_b32_e32 v216, v220
	v_permlane16_swap_b32_e32 v217, v221
	v_permlane16_swap_b32_e32 v218, v222
	v_permlane16_swap_b32_e32 v219, v223
	v_permlane16_swap_b32_e32 v224, v228
	v_permlane16_swap_b32_e32 v225, v229
	v_permlane16_swap_b32_e32 v226, v230
	v_permlane16_swap_b32_e32 v227, v231
	v_permlane32_swap_b32_e32 v216, v224
	v_permlane32_swap_b32_e32 v217, v225
	v_permlane32_swap_b32_e32 v218, v226
	v_permlane32_swap_b32_e32 v219, v227
	v_permlane32_swap_b32_e32 v220, v228
	v_permlane32_swap_b32_e32 v221, v229
	v_permlane32_swap_b32_e32 v222, v230
	v_permlane32_swap_b32_e32 v223, v231
	v_lshl_add_u64 v[234:235], v[142:143], 0, v[232:233]
	global_store_dwordx4 v[234:235], v[216:219], off
	global_store_dwordx4 v[234:235], v[220:223], off offset:64
	global_store_dwordx4 v[234:235], v[224:227], off offset:128
	global_store_dwordx4 v[234:235], v[228:231], off offset:192
	s_nop 1
	v_lshlrev_b64 v[114:115], 6, v[126:127]
	v_lshl_add_u64 v[142:143], s[6:7], 0, v[114:115]
	global_load_dwordx4 v[114:117], v[142:143], off
	global_load_dwordx4 v[118:121], v[142:143], off offset:16
	global_load_dwordx4 v[122:125], v[142:143], off offset:32
	global_load_dwordx4 v[152:155], v[142:143], off offset:48
	v_lshlrev_b64 v[142:143], 11, v[126:127]
	v_lshl_add_u64 v[156:157], s[8:9], 0, v[142:143]
	v_lshl_add_u64 v[142:143], s[0:1], 0, v[142:143]
	v_lshl_add_u64 v[164:165], v[156:157], 0, v[138:139]
	v_lshl_add_u64 v[142:143], v[142:143], 0, v[138:139]
	global_load_dwordx4 v[156:159], v[164:165], off
	global_load_dwordx4 v[160:163], v[142:143], off
	s_nop 0
	global_load_dwordx4 v[164:167], v[164:165], off offset:16
	s_nop 0
	global_load_dwordx4 v[168:171], v[142:143], off offset:16
	s_waitcnt vmcnt(7)
	v_mov_b32_e32 v142, v115
	v_mov_b32_e32 v143, v116
	v_mov_b32_e32 v115, v117
	s_waitcnt vmcnt(6)
	v_mov_b32_e32 v116, v119
	v_mov_b32_e32 v117, v120
	v_mov_b32_e32 v119, v121
	v_pk_add_f32 v[114:115], v[142:143], v[114:115]
	v_pk_add_f32 v[116:117], v[116:117], v[118:119]
	v_pk_add_f32 v[114:115], v[114:115], v[114:115] op_sel:[0,1] op_sel_hi:[1,0]
	v_pk_add_f32 v[116:117], v[116:117], v[116:117] op_sel:[0,1] op_sel_hi:[1,0]
	s_waitcnt vmcnt(5)
	v_add_f32_e32 v120, v122, v123
	v_add_f32_e32 v122, v124, v125
	s_waitcnt vmcnt(4)
	v_mov_b32_e32 v121, v154
	v_mov_b32_e32 v123, v155
	v_mov_b32_e32 v115, v152
	v_mov_b32_e32 v117, v153
	v_pk_add_f32 v[118:119], v[120:121], v[122:123]
	v_pk_add_f32 v[114:115], v[114:115], v[116:117]
	s_waitcnt vmcnt(2)
	v_lshlrev_b32_e32 v124, 16, v162
	v_pk_add_f32 v[114:115], v[114:115], v[118:119]
	v_and_b32_e32 v125, 0xffff0000, v162
	v_add_f32_e32 v114, v114, v115
	v_fmamk_f32 v114, v114, 0x3a800000, v150
	v_mul_f32_e32 v115, 0x4b800000, v114
	v_cmp_gt_f32_e32 vcc, s51, v114
	v_lshlrev_b32_e32 v152, 16, v163
	v_and_b32_e32 v153, 0xffff0000, v163
	v_cndmask_b32_e32 v114, v114, v115, vcc
	v_rsq_f32_e32 v116, v114
	v_lshlrev_b32_e32 v114, 16, v156
	v_and_b32_e32 v115, 0xffff0000, v156
	v_lshlrev_b32_e32 v118, 16, v157
	v_mul_f32_e32 v117, 0x45800000, v116
	v_cndmask_b32_e32 v116, v116, v117, vcc
	v_mul_f32_e32 v141, 0xbfb8aa3b, v116
	v_mul_f32_e32 v109, v109, v141
	v_mul_f32_e32 v96, v96, v141
	v_exp_f32_e32 v109, v109
	v_exp_f32_e32 v96, v96
	v_mul_f32_e32 v97, v97, v141
	v_exp_f32_e32 v97, v97
	v_add_f32_e32 v109, 1.0, v109
	v_add_f32_e32 v96, 1.0, v96
	v_mul_f32_e32 v108, v108, v141
	v_mul_f32_e32 v110, v110, v141
	v_rcp_f32_e32 v117, v109
	v_mul_f32_e32 v109, v111, v141
	v_rcp_f32_e32 v162, v96
	v_add_f32_e32 v96, 1.0, v97
	v_exp_f32_e32 v116, v108
	v_exp_f32_e32 v110, v110
	v_exp_f32_e32 v111, v109
	v_mul_f32_e32 v104, v104, v141
	v_mul_f32_e32 v105, v105, v141
	v_mul_f32_e32 v106, v106, v141
	v_mul_f32_e32 v107, v107, v141
	v_rcp_f32_e32 v163, v96
	v_mul_f32_e32 v96, v98, v141
	v_exp_f32_e32 v104, v104
	v_exp_f32_e32 v105, v105
	v_exp_f32_e32 v106, v106
	v_exp_f32_e32 v107, v107
	v_mul_f32_e32 v100, v100, v141
	v_mul_f32_e32 v101, v101, v141
	v_mul_f32_e32 v102, v102, v141
	v_mul_f32_e32 v103, v103, v141
	v_exp_f32_e32 v96, v96
	v_mul_f32_e32 v97, v99, v141
	v_exp_f32_e32 v100, v100
	v_exp_f32_e32 v101, v101
	v_exp_f32_e32 v102, v102
	v_exp_f32_e32 v103, v103
	v_exp_f32_e32 v97, v97
	v_add_f32_e32 v116, 1.0, v116
	v_add_f32_e32 v110, 1.0, v110
	v_add_f32_e32 v111, 1.0, v111
	v_rcp_f32_e32 v116, v116
	v_rcp_f32_e32 v110, v110
	v_rcp_f32_e32 v111, v111
	v_add_f32_e32 v104, 1.0, v104
	v_add_f32_e32 v105, 1.0, v105
	v_add_f32_e32 v106, 1.0, v106
	v_add_f32_e32 v107, 1.0, v107
	v_add_f32_e32 v96, 1.0, v96
	v_rcp_f32_e32 v104, v104
	v_rcp_f32_e32 v105, v105
	v_rcp_f32_e32 v106, v106
	v_rcp_f32_e32 v107, v107
	v_add_f32_e32 v100, 1.0, v100
	v_add_f32_e32 v101, 1.0, v101
	v_add_f32_e32 v102, 1.0, v102
	v_add_f32_e32 v103, 1.0, v103
	v_rcp_f32_e32 v172, v96
	v_add_f32_e32 v96, 1.0, v97
	v_rcp_f32_e32 v100, v100
	v_rcp_f32_e32 v101, v101
	v_rcp_f32_e32 v102, v102
	v_rcp_f32_e32 v103, v103
	v_rcp_f32_e32 v173, v96
	v_lshlrev_b64 v[96:97], 12, v[126:127]
	v_lshlrev_b32_e32 v108, 16, v160
	v_and_b32_e32 v109, 0xffff0000, v160
	v_and_b32_e32 v119, 0xffff0000, v157
	v_lshlrev_b32_e32 v120, 16, v161
	v_and_b32_e32 v121, 0xffff0000, v161
	v_lshl_add_u64 v[96:97], s[84:85], 0, v[96:97]
	v_lshlrev_b32_e32 v122, 16, v158
	v_and_b32_e32 v123, 0xffff0000, v158
	v_lshlrev_b32_e32 v142, 16, v159
	v_and_b32_e32 v143, 0xffff0000, v159
	v_lshl_add_u64 v[126:127], v[96:97], 0, v[112:113]
	v_pk_fma_f32 v[218:219], v[110:111], v[118:119], v[120:121]
	v_pk_fma_f32 v[216:217], v[116:117], v[114:115], v[108:109]
	s_waitcnt vmcnt(1)
	v_lshlrev_b32_e32 v154, 16, v164
	v_and_b32_e32 v155, 0xffff0000, v164
	s_waitcnt vmcnt(0)
	v_lshlrev_b32_e32 v156, 16, v168
	v_and_b32_e32 v157, 0xffff0000, v168
	v_lshlrev_b32_e32 v158, 16, v165
	v_and_b32_e32 v159, 0xffff0000, v165
	v_lshlrev_b32_e32 v160, 16, v169
	v_and_b32_e32 v161, 0xffff0000, v169
	v_lshlrev_b32_e32 v164, 16, v166
	v_and_b32_e32 v165, 0xffff0000, v166
	v_pk_fma_f32 v[222:223], v[106:107], v[142:143], v[152:153]
	v_pk_fma_f32 v[220:221], v[104:105], v[122:123], v[124:125]
	v_lshlrev_b32_e32 v168, 16, v170
	v_and_b32_e32 v169, 0xffff0000, v170
	v_lshlrev_b32_e32 v166, 16, v167
	v_and_b32_e32 v167, 0xffff0000, v167
	v_lshlrev_b32_e32 v170, 16, v171
	v_and_b32_e32 v171, 0xffff0000, v171
	s_nop 1
	v_pk_fma_f32 v[226:227], v[102:103], v[158:159], v[160:161]
	v_pk_fma_f32 v[224:225], v[100:101], v[154:155], v[156:157]
	s_nop 1
	v_pk_fma_f32 v[230:231], v[172:173], v[166:167], v[170:171]
	v_pk_fma_f32 v[228:229], v[162:163], v[164:165], v[168:169]
	s_nop 1
	v_permlane16_swap_b32_e32 v216, v220
	v_permlane16_swap_b32_e32 v217, v221
	v_permlane16_swap_b32_e32 v218, v222
	v_permlane16_swap_b32_e32 v219, v223
	v_permlane16_swap_b32_e32 v224, v228
	v_permlane16_swap_b32_e32 v225, v229
	v_permlane16_swap_b32_e32 v226, v230
	v_permlane16_swap_b32_e32 v227, v231
	v_permlane32_swap_b32_e32 v216, v224
	v_permlane32_swap_b32_e32 v217, v225
	v_permlane32_swap_b32_e32 v218, v226
	v_permlane32_swap_b32_e32 v219, v227
	v_permlane32_swap_b32_e32 v220, v228
	v_permlane32_swap_b32_e32 v221, v229
	v_permlane32_swap_b32_e32 v222, v230
	v_permlane32_swap_b32_e32 v223, v231
	v_lshl_add_u64 v[234:235], v[126:127], 0, v[232:233]
	global_store_dwordx4 v[234:235], v[216:219], off
	global_store_dwordx4 v[234:235], v[220:223], off offset:64
	global_store_dwordx4 v[234:235], v[224:227], off offset:128
	global_store_dwordx4 v[234:235], v[228:231], off offset:192
	v_or_b32_e32 v126, 32, v140
	v_ashrrev_i32_e32 v127, 31, v126
	v_lshlrev_b64 v[96:97], 6, v[126:127]
	v_lshl_add_u64 v[108:109], s[6:7], 0, v[96:97]
	global_load_dwordx4 v[96:99], v[108:109], off
	global_load_dwordx4 v[100:103], v[108:109], off offset:16
	global_load_dwordx4 v[104:107], v[108:109], off offset:32
	s_nop 0
	global_load_dwordx4 v[108:111], v[108:109], off offset:48
	v_lshlrev_b64 v[114:115], 11, v[126:127]
	v_lshl_add_u64 v[116:117], s[8:9], 0, v[114:115]
	v_lshl_add_u64 v[122:123], v[116:117], 0, v[138:139]
	v_lshl_add_u64 v[118:119], s[0:1], 0, v[114:115]
	global_load_dwordx4 v[114:117], v[122:123], off
	v_lshl_add_u64 v[142:143], v[118:119], 0, v[138:139]
	global_load_dwordx4 v[118:121], v[142:143], off
	s_nop 0
	global_load_dwordx4 v[122:125], v[122:123], off offset:16
	s_nop 0
	global_load_dwordx4 v[152:155], v[142:143], off offset:16
	s_waitcnt vmcnt(7)
	v_mov_b32_e32 v142, v97
	v_mov_b32_e32 v143, v98
	v_mov_b32_e32 v97, v99
	s_waitcnt vmcnt(6)
	v_mov_b32_e32 v98, v101
	v_mov_b32_e32 v99, v102
	v_mov_b32_e32 v101, v103
	v_pk_add_f32 v[96:97], v[142:143], v[96:97]
	v_pk_add_f32 v[98:99], v[98:99], v[100:101]
	v_pk_add_f32 v[96:97], v[96:97], v[96:97] op_sel:[0,1] op_sel_hi:[1,0]
	v_pk_add_f32 v[98:99], v[98:99], v[98:99] op_sel:[0,1] op_sel_hi:[1,0]
	s_waitcnt vmcnt(5)
	v_add_f32_e32 v100, v104, v105
	v_add_f32_e32 v102, v106, v107
	s_waitcnt vmcnt(4)
	v_mov_b32_e32 v97, v108
	v_mov_b32_e32 v99, v109
	v_mov_b32_e32 v101, v110
	v_mov_b32_e32 v103, v111
	v_pk_add_f32 v[96:97], v[96:97], v[98:99]
	v_pk_add_f32 v[98:99], v[100:101], v[102:103]
	s_waitcnt vmcnt(3)
	v_lshlrev_b32_e32 v100, 16, v115
	v_pk_add_f32 v[96:97], v[96:97], v[98:99]
	v_and_b32_e32 v101, 0xffff0000, v115
	v_add_f32_e32 v96, v96, v97
	v_fmamk_f32 v96, v96, 0x3a800000, v150
	v_mul_f32_e32 v97, 0x4b800000, v96
	v_cmp_gt_f32_e32 vcc, s51, v96
	s_waitcnt vmcnt(1)
	v_and_b32_e32 v115, 0xffff0000, v122
	v_lshlrev_b32_e32 v98, 16, v118
	v_cndmask_b32_e32 v96, v96, v97, vcc
	v_rsq_f32_e32 v96, v96
	v_and_b32_e32 v99, 0xffff0000, v118
	v_lshlrev_b32_e32 v102, 16, v119
	v_and_b32_e32 v103, 0xffff0000, v119
	v_mul_f32_e32 v97, 0x45800000, v96
	v_cndmask_b32_e32 v96, v96, v97, vcc
	v_mul_f32_e32 v141, 0xbfb8aa3b, v96
	v_mul_f32_e32 v80, v80, v141
	v_exp_f32_e32 v80, v80
	v_mul_f32_e32 v81, v81, v141
	v_exp_f32_e32 v81, v81
	v_mul_f32_e32 v92, v92, v141
	v_add_f32_e32 v80, 1.0, v80
	v_mul_f32_e32 v93, v93, v141
	v_lshlrev_b32_e32 v96, 16, v114
	v_and_b32_e32 v97, 0xffff0000, v114
	v_mul_f32_e32 v94, v94, v141
	v_mul_f32_e32 v95, v95, v141
	v_lshlrev_b32_e32 v114, 16, v122
	v_rcp_f32_e32 v122, v80
	v_add_f32_e32 v80, 1.0, v81
	v_exp_f32_e32 v92, v92
	v_exp_f32_e32 v93, v93
	v_exp_f32_e32 v94, v94
	v_exp_f32_e32 v95, v95
	v_mul_f32_e32 v88, v88, v141
	v_mul_f32_e32 v89, v89, v141
	v_mul_f32_e32 v90, v90, v141
	v_mul_f32_e32 v91, v91, v141
	v_lshlrev_b32_e32 v118, 16, v123
	v_and_b32_e32 v119, 0xffff0000, v123
	v_rcp_f32_e32 v123, v80
	v_mul_f32_e32 v80, v82, v141
	v_exp_f32_e32 v88, v88
	v_exp_f32_e32 v89, v89
	v_exp_f32_e32 v90, v90
	v_exp_f32_e32 v91, v91
	v_mul_f32_e32 v84, v84, v141
	v_mul_f32_e32 v85, v85, v141
	v_mul_f32_e32 v86, v86, v141
	v_mul_f32_e32 v87, v87, v141
	v_exp_f32_e32 v80, v80
	v_mul_f32_e32 v81, v83, v141
	v_exp_f32_e32 v84, v84
	v_exp_f32_e32 v85, v85
	v_exp_f32_e32 v86, v86
	v_exp_f32_e32 v87, v87
	v_exp_f32_e32 v81, v81
	v_add_f32_e32 v92, 1.0, v92
	v_add_f32_e32 v93, 1.0, v93
	v_add_f32_e32 v94, 1.0, v94
	v_add_f32_e32 v95, 1.0, v95
	v_rcp_f32_e32 v92, v92
	v_rcp_f32_e32 v93, v93
	v_rcp_f32_e32 v94, v94
	v_rcp_f32_e32 v95, v95
	v_add_f32_e32 v88, 1.0, v88
	v_add_f32_e32 v89, 1.0, v89
	v_add_f32_e32 v90, 1.0, v90
	v_add_f32_e32 v91, 1.0, v91
	v_add_f32_e32 v80, 1.0, v80
	v_rcp_f32_e32 v88, v88
	v_rcp_f32_e32 v89, v89
	v_rcp_f32_e32 v90, v90
	v_rcp_f32_e32 v91, v91
	v_add_f32_e32 v84, 1.0, v84
	v_add_f32_e32 v85, 1.0, v85
	v_add_f32_e32 v86, 1.0, v86
	v_add_f32_e32 v87, 1.0, v87
	v_rcp_f32_e32 v156, v80
	v_add_f32_e32 v80, 1.0, v81
	v_rcp_f32_e32 v84, v84
	v_rcp_f32_e32 v85, v85
	v_rcp_f32_e32 v86, v86
	v_rcp_f32_e32 v87, v87
	v_rcp_f32_e32 v157, v80
	v_lshlrev_b64 v[80:81], 12, v[126:127]
	v_lshl_add_u64 v[80:81], s[84:85], 0, v[80:81]
	v_lshlrev_b32_e32 v104, 16, v116
	v_and_b32_e32 v105, 0xffff0000, v116
	v_lshlrev_b32_e32 v106, 16, v120
	v_and_b32_e32 v107, 0xffff0000, v120
	v_lshlrev_b32_e32 v108, 16, v117
	v_and_b32_e32 v109, 0xffff0000, v117
	v_lshlrev_b32_e32 v110, 16, v121
	v_and_b32_e32 v111, 0xffff0000, v121
	v_lshl_add_u64 v[126:127], v[80:81], 0, v[112:113]
	v_pk_fma_f32 v[218:219], v[94:95], v[100:101], v[102:103]
	v_pk_fma_f32 v[216:217], v[92:93], v[96:97], v[98:99]
	s_waitcnt vmcnt(0)
	v_lshlrev_b32_e32 v116, 16, v152
	v_and_b32_e32 v117, 0xffff0000, v152
	v_lshlrev_b32_e32 v120, 16, v153
	v_and_b32_e32 v121, 0xffff0000, v153
	v_lshlrev_b32_e32 v142, 16, v124
	v_and_b32_e32 v143, 0xffff0000, v124
	v_pk_fma_f32 v[222:223], v[90:91], v[108:109], v[110:111]
	v_pk_fma_f32 v[220:221], v[88:89], v[104:105], v[106:107]
	v_lshlrev_b32_e32 v152, 16, v154
	v_and_b32_e32 v153, 0xffff0000, v154
	v_lshlrev_b32_e32 v124, 16, v125
	v_and_b32_e32 v125, 0xffff0000, v125
	v_lshlrev_b32_e32 v154, 16, v155
	v_and_b32_e32 v155, 0xffff0000, v155
	s_nop 1
	v_pk_fma_f32 v[226:227], v[86:87], v[118:119], v[120:121]
	v_pk_fma_f32 v[224:225], v[84:85], v[114:115], v[116:117]
	v_or_b32_e32 v114, 48, v140
	v_ashrrev_i32_e32 v115, 31, v114
	s_nop 0
	v_pk_fma_f32 v[230:231], v[156:157], v[124:125], v[154:155]
	v_pk_fma_f32 v[228:229], v[122:123], v[142:143], v[152:153]
	s_nop 1
	v_permlane16_swap_b32_e32 v216, v220
	v_permlane16_swap_b32_e32 v217, v221
	v_permlane16_swap_b32_e32 v218, v222
	v_permlane16_swap_b32_e32 v219, v223
	v_permlane16_swap_b32_e32 v224, v228
	v_permlane16_swap_b32_e32 v225, v229
	v_permlane16_swap_b32_e32 v226, v230
	v_permlane16_swap_b32_e32 v227, v231
	v_permlane32_swap_b32_e32 v216, v224
	v_permlane32_swap_b32_e32 v217, v225
	v_permlane32_swap_b32_e32 v218, v226
	v_permlane32_swap_b32_e32 v219, v227
	v_permlane32_swap_b32_e32 v220, v228
	v_permlane32_swap_b32_e32 v221, v229
	v_permlane32_swap_b32_e32 v222, v230
	v_permlane32_swap_b32_e32 v223, v231
	v_lshl_add_u64 v[234:235], v[126:127], 0, v[232:233]
	global_store_dwordx4 v[234:235], v[216:219], off
	global_store_dwordx4 v[234:235], v[220:223], off offset:64
	global_store_dwordx4 v[234:235], v[224:227], off offset:128
	global_store_dwordx4 v[234:235], v[228:231], off offset:192
	s_nop 1
	v_lshlrev_b64 v[80:81], 6, v[114:115]
	v_lshl_add_u64 v[96:97], s[6:7], 0, v[80:81]
	global_load_dwordx4 v[80:83], v[96:97], off
	global_load_dwordx4 v[84:87], v[96:97], off offset:16
	global_load_dwordx4 v[88:91], v[96:97], off offset:32
	global_load_dwordx4 v[92:95], v[96:97], off offset:48
	v_lshlrev_b64 v[96:97], 11, v[114:115]
	v_lshl_add_u64 v[98:99], s[8:9], 0, v[96:97]
	v_lshl_add_u64 v[104:105], v[98:99], 0, v[138:139]
	v_lshl_add_u64 v[100:101], s[0:1], 0, v[96:97]
	global_load_dwordx4 v[96:99], v[104:105], off
	v_lshl_add_u64 v[108:109], v[100:101], 0, v[138:139]
	global_load_dwordx4 v[100:103], v[108:109], off
	s_nop 0
	global_load_dwordx4 v[104:107], v[104:105], off offset:16
	s_nop 0
	global_load_dwordx4 v[108:111], v[108:109], off offset:16
	s_waitcnt vmcnt(7)
	v_mov_b32_e32 v116, v81
	v_mov_b32_e32 v117, v82
	v_mov_b32_e32 v81, v83
	s_waitcnt vmcnt(6)
	v_mov_b32_e32 v82, v85
	v_mov_b32_e32 v83, v86
	v_mov_b32_e32 v85, v87
	v_pk_add_f32 v[80:81], v[116:117], v[80:81]
	v_pk_add_f32 v[82:83], v[82:83], v[84:85]
	v_pk_add_f32 v[80:81], v[80:81], v[80:81] op_sel:[0,1] op_sel_hi:[1,0]
	v_pk_add_f32 v[82:83], v[82:83], v[82:83] op_sel:[0,1] op_sel_hi:[1,0]
	s_waitcnt vmcnt(5)
	v_add_f32_e32 v84, v88, v89
	v_add_f32_e32 v86, v90, v91
	s_waitcnt vmcnt(4)
	v_mov_b32_e32 v81, v92
	v_mov_b32_e32 v83, v93
	v_mov_b32_e32 v85, v94
	v_mov_b32_e32 v87, v95
	v_pk_add_f32 v[80:81], v[80:81], v[82:83]
	v_pk_add_f32 v[82:83], v[84:85], v[86:87]
	s_waitcnt vmcnt(3)
	v_lshlrev_b32_e32 v84, 16, v97
	v_pk_add_f32 v[80:81], v[80:81], v[82:83]
	v_and_b32_e32 v85, 0xffff0000, v97
	v_add_f32_e32 v80, v80, v81
	v_fmamk_f32 v80, v80, 0x3a800000, v150
	v_mul_f32_e32 v81, 0x4b800000, v80
	v_cmp_gt_f32_e32 vcc, s51, v80
	s_waitcnt vmcnt(1)
	v_and_b32_e32 v97, 0xffff0000, v104
	v_lshlrev_b32_e32 v82, 16, v100
	v_cndmask_b32_e32 v80, v80, v81, vcc
	v_rsq_f32_e32 v80, v80
	v_and_b32_e32 v83, 0xffff0000, v100
	v_lshlrev_b32_e32 v86, 16, v101
	v_and_b32_e32 v87, 0xffff0000, v101
	v_mul_f32_e32 v81, 0x45800000, v80
	v_cndmask_b32_e32 v80, v80, v81, vcc
	v_mul_f32_e32 v117, 0xbfb8aa3b, v80
	v_mul_f32_e32 v64, v64, v117
	v_exp_f32_e32 v64, v64
	v_mul_f32_e32 v65, v65, v117
	v_exp_f32_e32 v65, v65
	v_mul_f32_e32 v76, v76, v117
	v_add_f32_e32 v64, 1.0, v64
	v_mul_f32_e32 v77, v77, v117
	v_lshlrev_b32_e32 v80, 16, v96
	v_and_b32_e32 v81, 0xffff0000, v96
	v_mul_f32_e32 v78, v78, v117
	v_mul_f32_e32 v79, v79, v117
	v_lshlrev_b32_e32 v96, 16, v104
	v_rcp_f32_e32 v104, v64
	v_add_f32_e32 v64, 1.0, v65
	v_exp_f32_e32 v76, v76
	v_exp_f32_e32 v77, v77
	v_exp_f32_e32 v78, v78
	v_exp_f32_e32 v79, v79
	v_mul_f32_e32 v72, v72, v117
	v_mul_f32_e32 v73, v73, v117
	v_mul_f32_e32 v74, v74, v117
	v_mul_f32_e32 v75, v75, v117
	v_lshlrev_b32_e32 v100, 16, v105
	v_and_b32_e32 v101, 0xffff0000, v105
	v_rcp_f32_e32 v105, v64
	v_mul_f32_e32 v64, v66, v117
	v_exp_f32_e32 v72, v72
	v_exp_f32_e32 v73, v73
	v_exp_f32_e32 v74, v74
	v_exp_f32_e32 v75, v75
	v_mul_f32_e32 v68, v68, v117
	v_mul_f32_e32 v69, v69, v117
	v_mul_f32_e32 v70, v70, v117
	v_mul_f32_e32 v71, v71, v117
	v_exp_f32_e32 v64, v64
	v_mul_f32_e32 v65, v67, v117
	v_exp_f32_e32 v68, v68
	v_exp_f32_e32 v69, v69
	v_exp_f32_e32 v70, v70
	v_exp_f32_e32 v71, v71
	v_exp_f32_e32 v65, v65
	v_add_f32_e32 v76, 1.0, v76
	v_add_f32_e32 v77, 1.0, v77
	v_add_f32_e32 v78, 1.0, v78
	v_add_f32_e32 v79, 1.0, v79
	v_rcp_f32_e32 v76, v76
	v_rcp_f32_e32 v77, v77
	v_rcp_f32_e32 v78, v78
	v_rcp_f32_e32 v79, v79
	v_add_f32_e32 v72, 1.0, v72
	v_add_f32_e32 v73, 1.0, v73
	v_add_f32_e32 v74, 1.0, v74
	v_add_f32_e32 v75, 1.0, v75
	v_add_f32_e32 v64, 1.0, v64
	v_rcp_f32_e32 v72, v72
	v_rcp_f32_e32 v73, v73
	v_rcp_f32_e32 v74, v74
	v_rcp_f32_e32 v75, v75
	v_add_f32_e32 v68, 1.0, v68
	v_add_f32_e32 v69, 1.0, v69
	v_add_f32_e32 v70, 1.0, v70
	v_add_f32_e32 v71, 1.0, v71
	v_rcp_f32_e32 v118, v64
	v_add_f32_e32 v64, 1.0, v65
	v_rcp_f32_e32 v68, v68
	v_rcp_f32_e32 v69, v69
	v_rcp_f32_e32 v70, v70
	v_rcp_f32_e32 v71, v71
	v_rcp_f32_e32 v119, v64
	v_lshlrev_b64 v[64:65], 12, v[114:115]
	v_lshl_add_u64 v[64:65], s[84:85], 0, v[64:65]
	v_lshlrev_b32_e32 v88, 16, v98
	v_and_b32_e32 v89, 0xffff0000, v98
	v_lshlrev_b32_e32 v90, 16, v102
	v_and_b32_e32 v91, 0xffff0000, v102
	v_lshlrev_b32_e32 v92, 16, v99
	v_and_b32_e32 v93, 0xffff0000, v99
	v_lshlrev_b32_e32 v94, 16, v103
	v_and_b32_e32 v95, 0xffff0000, v103
	v_lshl_add_u64 v[114:115], v[64:65], 0, v[112:113]
	v_pk_fma_f32 v[218:219], v[78:79], v[84:85], v[86:87]
	v_pk_fma_f32 v[216:217], v[76:77], v[80:81], v[82:83]
	s_waitcnt vmcnt(0)
	v_lshlrev_b32_e32 v98, 16, v108
	v_and_b32_e32 v99, 0xffff0000, v108
	v_lshlrev_b32_e32 v102, 16, v109
	v_and_b32_e32 v103, 0xffff0000, v109
	v_lshlrev_b32_e32 v108, 16, v106
	v_and_b32_e32 v109, 0xffff0000, v106
	v_pk_fma_f32 v[222:223], v[74:75], v[92:93], v[94:95]
	v_pk_fma_f32 v[220:221], v[72:73], v[88:89], v[90:91]
	v_lshlrev_b32_e32 v116, 16, v110
	v_and_b32_e32 v117, 0xffff0000, v110
	v_lshlrev_b32_e32 v106, 16, v107
	v_and_b32_e32 v107, 0xffff0000, v107
	v_lshlrev_b32_e32 v110, 16, v111
	v_and_b32_e32 v111, 0xffff0000, v111
	s_nop 1
	v_pk_fma_f32 v[226:227], v[70:71], v[100:101], v[102:103]
	v_pk_fma_f32 v[224:225], v[68:69], v[96:97], v[98:99]
	v_add_u32_e32 v96, 0x80, v140
	v_ashrrev_i32_e32 v97, 31, v96
	s_nop 0
	v_pk_fma_f32 v[230:231], v[118:119], v[106:107], v[110:111]
	v_pk_fma_f32 v[228:229], v[104:105], v[108:109], v[116:117]
	s_nop 1
	v_permlane16_swap_b32_e32 v216, v220
	v_permlane16_swap_b32_e32 v217, v221
	v_permlane16_swap_b32_e32 v218, v222
	v_permlane16_swap_b32_e32 v219, v223
	v_permlane16_swap_b32_e32 v224, v228
	v_permlane16_swap_b32_e32 v225, v229
	v_permlane16_swap_b32_e32 v226, v230
	v_permlane16_swap_b32_e32 v227, v231
	v_permlane32_swap_b32_e32 v216, v224
	v_permlane32_swap_b32_e32 v217, v225
	v_permlane32_swap_b32_e32 v218, v226
	v_permlane32_swap_b32_e32 v219, v227
	v_permlane32_swap_b32_e32 v220, v228
	v_permlane32_swap_b32_e32 v221, v229
	v_permlane32_swap_b32_e32 v222, v230
	v_permlane32_swap_b32_e32 v223, v231
	v_lshl_add_u64 v[234:235], v[114:115], 0, v[232:233]
	global_store_dwordx4 v[234:235], v[216:219], off
	global_store_dwordx4 v[234:235], v[220:223], off offset:64
	global_store_dwordx4 v[234:235], v[224:227], off offset:128
	global_store_dwordx4 v[234:235], v[228:231], off offset:192
	s_nop 1
	v_lshlrev_b64 v[64:65], 6, v[96:97]
	v_lshl_add_u64 v[80:81], s[6:7], 0, v[64:65]
	global_load_dwordx4 v[64:67], v[80:81], off
	global_load_dwordx4 v[68:71], v[80:81], off offset:16
	global_load_dwordx4 v[72:75], v[80:81], off offset:32
	global_load_dwordx4 v[76:79], v[80:81], off offset:48
	v_lshlrev_b64 v[80:81], 11, v[96:97]
	v_lshl_add_u64 v[82:83], s[8:9], 0, v[80:81]
	v_lshl_add_u64 v[98:99], v[82:83], 0, v[138:139]
	v_lshl_add_u64 v[84:85], s[0:1], 0, v[80:81]
	global_load_dwordx4 v[80:83], v[98:99], off
	v_lshl_add_u64 v[100:101], v[84:85], 0, v[138:139]
	global_load_dwordx4 v[84:87], v[100:101], off
	global_load_dwordx4 v[88:91], v[98:99], off offset:16
	global_load_dwordx4 v[92:95], v[100:101], off offset:16
	s_waitcnt vmcnt(7)
	v_mov_b32_e32 v98, v65
	v_mov_b32_e32 v99, v66
	v_mov_b32_e32 v65, v67
	s_waitcnt vmcnt(6)
	v_mov_b32_e32 v66, v69
	v_mov_b32_e32 v67, v70
	v_mov_b32_e32 v69, v71
	v_pk_add_f32 v[64:65], v[98:99], v[64:65]
	v_pk_add_f32 v[66:67], v[66:67], v[68:69]
	v_pk_add_f32 v[64:65], v[64:65], v[64:65] op_sel:[0,1] op_sel_hi:[1,0]
	v_pk_add_f32 v[66:67], v[66:67], v[66:67] op_sel:[0,1] op_sel_hi:[1,0]
	s_waitcnt vmcnt(5)
	v_add_f32_e32 v68, v72, v73
	v_add_f32_e32 v70, v74, v75
	s_waitcnt vmcnt(4)
	v_mov_b32_e32 v65, v76
	v_mov_b32_e32 v67, v77
	v_mov_b32_e32 v69, v78
	v_mov_b32_e32 v71, v79
	v_pk_add_f32 v[64:65], v[64:65], v[66:67]
	v_pk_add_f32 v[66:67], v[68:69], v[70:71]
	s_waitcnt vmcnt(3)
	v_lshlrev_b32_e32 v68, 16, v81
	v_pk_add_f32 v[64:65], v[64:65], v[66:67]
	v_and_b32_e32 v69, 0xffff0000, v81
	v_add_f32_e32 v64, v64, v65
	v_fmamk_f32 v64, v64, 0x3a800000, v150
	v_mul_f32_e32 v65, 0x4b800000, v64
	v_cmp_gt_f32_e32 vcc, s51, v64
	s_waitcnt vmcnt(1)
	v_and_b32_e32 v81, 0xffff0000, v88
	v_lshlrev_b32_e32 v66, 16, v84
	v_cndmask_b32_e32 v64, v64, v65, vcc
	v_rsq_f32_e32 v64, v64
	v_and_b32_e32 v67, 0xffff0000, v84
	v_lshlrev_b32_e32 v70, 16, v85
	v_and_b32_e32 v71, 0xffff0000, v85
	v_mul_f32_e32 v65, 0x45800000, v64
	v_cndmask_b32_e32 v64, v64, v65, vcc
	v_mul_f32_e32 v99, 0xbfb8aa3b, v64
	v_mul_f32_e32 v48, v48, v99
	v_exp_f32_e32 v48, v48
	v_mul_f32_e32 v49, v49, v99
	v_exp_f32_e32 v49, v49
	v_mul_f32_e32 v60, v60, v99
	v_add_f32_e32 v48, 1.0, v48
	v_mul_f32_e32 v61, v61, v99
	v_lshlrev_b32_e32 v64, 16, v80
	v_and_b32_e32 v65, 0xffff0000, v80
	v_mul_f32_e32 v62, v62, v99
	v_mul_f32_e32 v63, v63, v99
	v_lshlrev_b32_e32 v80, 16, v88
	v_rcp_f32_e32 v88, v48
	v_add_f32_e32 v48, 1.0, v49
	v_exp_f32_e32 v60, v60
	v_exp_f32_e32 v61, v61
	v_exp_f32_e32 v62, v62
	v_exp_f32_e32 v63, v63
	v_mul_f32_e32 v56, v56, v99
	v_mul_f32_e32 v57, v57, v99
	v_mul_f32_e32 v58, v58, v99
	v_mul_f32_e32 v59, v59, v99
	v_lshlrev_b32_e32 v84, 16, v89
	v_and_b32_e32 v85, 0xffff0000, v89
	v_rcp_f32_e32 v89, v48
	v_mul_f32_e32 v48, v50, v99
	v_exp_f32_e32 v56, v56
	v_exp_f32_e32 v57, v57
	v_exp_f32_e32 v58, v58
	v_exp_f32_e32 v59, v59
	v_mul_f32_e32 v52, v52, v99
	v_mul_f32_e32 v53, v53, v99
	v_mul_f32_e32 v54, v54, v99
	v_mul_f32_e32 v55, v55, v99
	v_exp_f32_e32 v48, v48
	v_mul_f32_e32 v49, v51, v99
	v_exp_f32_e32 v52, v52
	v_exp_f32_e32 v53, v53
	v_exp_f32_e32 v54, v54
	v_exp_f32_e32 v55, v55
	v_exp_f32_e32 v49, v49
	v_add_f32_e32 v60, 1.0, v60
	v_add_f32_e32 v61, 1.0, v61
	v_add_f32_e32 v62, 1.0, v62
	v_add_f32_e32 v63, 1.0, v63
	v_rcp_f32_e32 v60, v60
	v_rcp_f32_e32 v61, v61
	v_rcp_f32_e32 v62, v62
	v_rcp_f32_e32 v63, v63
	v_add_f32_e32 v56, 1.0, v56
	v_add_f32_e32 v57, 1.0, v57
	v_add_f32_e32 v58, 1.0, v58
	v_add_f32_e32 v59, 1.0, v59
	v_add_f32_e32 v48, 1.0, v48
	v_rcp_f32_e32 v56, v56
	v_rcp_f32_e32 v57, v57
	v_rcp_f32_e32 v58, v58
	v_rcp_f32_e32 v59, v59
	v_add_f32_e32 v52, 1.0, v52
	v_add_f32_e32 v53, 1.0, v53
	v_add_f32_e32 v54, 1.0, v54
	v_add_f32_e32 v55, 1.0, v55
	v_rcp_f32_e32 v100, v48
	v_add_f32_e32 v48, 1.0, v49
	v_rcp_f32_e32 v52, v52
	v_rcp_f32_e32 v53, v53
	v_rcp_f32_e32 v54, v54
	v_rcp_f32_e32 v55, v55
	v_rcp_f32_e32 v101, v48
	v_lshlrev_b64 v[48:49], 12, v[96:97]
	v_lshl_add_u64 v[48:49], s[84:85], 0, v[48:49]
	v_lshlrev_b32_e32 v72, 16, v82
	v_and_b32_e32 v73, 0xffff0000, v82
	v_lshlrev_b32_e32 v74, 16, v86
	v_and_b32_e32 v75, 0xffff0000, v86
	v_lshlrev_b32_e32 v76, 16, v83
	v_and_b32_e32 v77, 0xffff0000, v83
	v_lshlrev_b32_e32 v78, 16, v87
	v_and_b32_e32 v79, 0xffff0000, v87
	v_lshl_add_u64 v[96:97], v[48:49], 0, v[112:113]
	v_pk_fma_f32 v[218:219], v[62:63], v[68:69], v[70:71]
	v_pk_fma_f32 v[216:217], v[60:61], v[64:65], v[66:67]
	s_waitcnt vmcnt(0)
	v_lshlrev_b32_e32 v82, 16, v92
	v_and_b32_e32 v83, 0xffff0000, v92
	v_lshlrev_b32_e32 v86, 16, v93
	v_and_b32_e32 v87, 0xffff0000, v93
	v_lshlrev_b32_e32 v92, 16, v90
	v_and_b32_e32 v93, 0xffff0000, v90
	v_pk_fma_f32 v[222:223], v[58:59], v[76:77], v[78:79]
	v_pk_fma_f32 v[220:221], v[56:57], v[72:73], v[74:75]
	v_lshlrev_b32_e32 v98, 16, v94
	v_and_b32_e32 v99, 0xffff0000, v94
	v_lshlrev_b32_e32 v90, 16, v91
	v_and_b32_e32 v91, 0xffff0000, v91
	v_lshlrev_b32_e32 v94, 16, v95
	v_and_b32_e32 v95, 0xffff0000, v95
	s_nop 1
	v_pk_fma_f32 v[226:227], v[54:55], v[84:85], v[86:87]
	v_pk_fma_f32 v[224:225], v[52:53], v[80:81], v[82:83]
	v_add_u32_e32 v80, 0x90, v140
	v_ashrrev_i32_e32 v81, 31, v80
	s_nop 0
	v_pk_fma_f32 v[230:231], v[100:101], v[90:91], v[94:95]
	v_pk_fma_f32 v[228:229], v[88:89], v[92:93], v[98:99]
	s_nop 1
	v_permlane16_swap_b32_e32 v216, v220
	v_permlane16_swap_b32_e32 v217, v221
	v_permlane16_swap_b32_e32 v218, v222
	v_permlane16_swap_b32_e32 v219, v223
	v_permlane16_swap_b32_e32 v224, v228
	v_permlane16_swap_b32_e32 v225, v229
	v_permlane16_swap_b32_e32 v226, v230
	v_permlane16_swap_b32_e32 v227, v231
	v_permlane32_swap_b32_e32 v216, v224
	v_permlane32_swap_b32_e32 v217, v225
	v_permlane32_swap_b32_e32 v218, v226
	v_permlane32_swap_b32_e32 v219, v227
	v_permlane32_swap_b32_e32 v220, v228
	v_permlane32_swap_b32_e32 v221, v229
	v_permlane32_swap_b32_e32 v222, v230
	v_permlane32_swap_b32_e32 v223, v231
	v_lshl_add_u64 v[234:235], v[96:97], 0, v[232:233]
	global_store_dwordx4 v[234:235], v[216:219], off
	global_store_dwordx4 v[234:235], v[220:223], off offset:64
	global_store_dwordx4 v[234:235], v[224:227], off offset:128
	global_store_dwordx4 v[234:235], v[228:231], off offset:192
	s_nop 1
	v_lshlrev_b64 v[48:49], 6, v[80:81]
	v_lshl_add_u64 v[64:65], s[6:7], 0, v[48:49]
	global_load_dwordx4 v[48:51], v[64:65], off
	global_load_dwordx4 v[52:55], v[64:65], off offset:16
	global_load_dwordx4 v[56:59], v[64:65], off offset:32
	global_load_dwordx4 v[60:63], v[64:65], off offset:48
	v_lshlrev_b64 v[64:65], 11, v[80:81]
	v_lshl_add_u64 v[66:67], s[8:9], 0, v[64:65]
	v_lshl_add_u64 v[82:83], v[66:67], 0, v[138:139]
	v_lshl_add_u64 v[68:69], s[0:1], 0, v[64:65]
	global_load_dwordx4 v[64:67], v[82:83], off
	v_lshl_add_u64 v[84:85], v[68:69], 0, v[138:139]
	global_load_dwordx4 v[68:71], v[84:85], off
	global_load_dwordx4 v[72:75], v[82:83], off offset:16
	global_load_dwordx4 v[76:79], v[84:85], off offset:16
	s_waitcnt vmcnt(7)
	v_mov_b32_e32 v82, v49
	v_mov_b32_e32 v83, v50
	v_mov_b32_e32 v49, v51
	s_waitcnt vmcnt(6)
	v_mov_b32_e32 v50, v53
	v_mov_b32_e32 v51, v54
	v_mov_b32_e32 v53, v55
	v_pk_add_f32 v[48:49], v[82:83], v[48:49]
	v_pk_add_f32 v[50:51], v[50:51], v[52:53]
	v_pk_add_f32 v[48:49], v[48:49], v[48:49] op_sel:[0,1] op_sel_hi:[1,0]
	v_pk_add_f32 v[50:51], v[50:51], v[50:51] op_sel:[0,1] op_sel_hi:[1,0]
	s_waitcnt vmcnt(5)
	v_add_f32_e32 v52, v56, v57
	v_add_f32_e32 v54, v58, v59
	s_waitcnt vmcnt(4)
	v_mov_b32_e32 v49, v60
	v_mov_b32_e32 v51, v61
	v_mov_b32_e32 v53, v62
	v_mov_b32_e32 v55, v63
	v_pk_add_f32 v[48:49], v[48:49], v[50:51]
	v_pk_add_f32 v[50:51], v[52:53], v[54:55]
	s_waitcnt vmcnt(3)
	v_lshlrev_b32_e32 v52, 16, v65
	v_pk_add_f32 v[48:49], v[48:49], v[50:51]
	v_and_b32_e32 v53, 0xffff0000, v65
	v_add_f32_e32 v48, v48, v49
	v_fmamk_f32 v48, v48, 0x3a800000, v150
	v_mul_f32_e32 v49, 0x4b800000, v48
	v_cmp_gt_f32_e32 vcc, s51, v48
	s_waitcnt vmcnt(1)
	v_and_b32_e32 v65, 0xffff0000, v72
	v_lshlrev_b32_e32 v50, 16, v68
	v_cndmask_b32_e32 v48, v48, v49, vcc
	v_rsq_f32_e32 v48, v48
	v_and_b32_e32 v51, 0xffff0000, v68
	v_lshlrev_b32_e32 v54, 16, v69
	v_and_b32_e32 v55, 0xffff0000, v69
	v_mul_f32_e32 v49, 0x45800000, v48
	v_cndmask_b32_e32 v48, v48, v49, vcc
	v_mul_f32_e32 v83, 0xbfb8aa3b, v48
	v_mul_f32_e32 v32, v32, v83
	v_exp_f32_e32 v32, v32
	v_mul_f32_e32 v33, v33, v83
	v_exp_f32_e32 v33, v33
	v_mul_f32_e32 v44, v44, v83
	v_add_f32_e32 v32, 1.0, v32
	v_mul_f32_e32 v45, v45, v83
	v_lshlrev_b32_e32 v48, 16, v64
	v_and_b32_e32 v49, 0xffff0000, v64
	v_mul_f32_e32 v46, v46, v83
	v_mul_f32_e32 v47, v47, v83
	v_lshlrev_b32_e32 v64, 16, v72
	v_rcp_f32_e32 v72, v32
	v_add_f32_e32 v32, 1.0, v33
	v_exp_f32_e32 v44, v44
	v_exp_f32_e32 v45, v45
	v_exp_f32_e32 v46, v46
	v_exp_f32_e32 v47, v47
	v_mul_f32_e32 v40, v40, v83
	v_mul_f32_e32 v41, v41, v83
	v_mul_f32_e32 v42, v42, v83
	v_mul_f32_e32 v43, v43, v83
	v_lshlrev_b32_e32 v68, 16, v73
	v_and_b32_e32 v69, 0xffff0000, v73
	v_rcp_f32_e32 v73, v32
	v_mul_f32_e32 v32, v34, v83
	v_exp_f32_e32 v40, v40
	v_exp_f32_e32 v41, v41
	v_exp_f32_e32 v42, v42
	v_exp_f32_e32 v43, v43
	v_mul_f32_e32 v36, v36, v83
	v_mul_f32_e32 v37, v37, v83
	v_mul_f32_e32 v38, v38, v83
	v_mul_f32_e32 v39, v39, v83
	v_exp_f32_e32 v32, v32
	v_mul_f32_e32 v33, v35, v83
	v_exp_f32_e32 v36, v36
	v_exp_f32_e32 v37, v37
	v_exp_f32_e32 v38, v38
	v_exp_f32_e32 v39, v39
	v_exp_f32_e32 v33, v33
	v_add_f32_e32 v44, 1.0, v44
	v_add_f32_e32 v45, 1.0, v45
	v_add_f32_e32 v46, 1.0, v46
	v_add_f32_e32 v47, 1.0, v47
	v_rcp_f32_e32 v44, v44
	v_rcp_f32_e32 v45, v45
	v_rcp_f32_e32 v46, v46
	v_rcp_f32_e32 v47, v47
	v_add_f32_e32 v40, 1.0, v40
	v_add_f32_e32 v41, 1.0, v41
	v_add_f32_e32 v42, 1.0, v42
	v_add_f32_e32 v43, 1.0, v43
	v_add_f32_e32 v32, 1.0, v32
	v_rcp_f32_e32 v40, v40
	v_rcp_f32_e32 v41, v41
	v_rcp_f32_e32 v42, v42
	v_rcp_f32_e32 v43, v43
	v_add_f32_e32 v36, 1.0, v36
	v_add_f32_e32 v37, 1.0, v37
	v_add_f32_e32 v38, 1.0, v38
	v_add_f32_e32 v39, 1.0, v39
	v_rcp_f32_e32 v84, v32
	v_add_f32_e32 v32, 1.0, v33
	v_rcp_f32_e32 v36, v36
	v_rcp_f32_e32 v37, v37
	v_rcp_f32_e32 v38, v38
	v_rcp_f32_e32 v39, v39
	v_rcp_f32_e32 v85, v32
	v_lshlrev_b64 v[32:33], 12, v[80:81]
	v_lshl_add_u64 v[32:33], s[84:85], 0, v[32:33]
	v_lshlrev_b32_e32 v56, 16, v66
	v_and_b32_e32 v57, 0xffff0000, v66
	v_lshlrev_b32_e32 v58, 16, v70
	v_and_b32_e32 v59, 0xffff0000, v70
	v_lshlrev_b32_e32 v60, 16, v67
	v_and_b32_e32 v61, 0xffff0000, v67
	v_lshlrev_b32_e32 v62, 16, v71
	v_and_b32_e32 v63, 0xffff0000, v71
	v_lshl_add_u64 v[80:81], v[32:33], 0, v[112:113]
	v_pk_fma_f32 v[218:219], v[46:47], v[52:53], v[54:55]
	v_pk_fma_f32 v[216:217], v[44:45], v[48:49], v[50:51]
	s_waitcnt vmcnt(0)
	v_lshlrev_b32_e32 v66, 16, v76
	v_and_b32_e32 v67, 0xffff0000, v76
	v_lshlrev_b32_e32 v70, 16, v77
	v_and_b32_e32 v71, 0xffff0000, v77
	v_lshlrev_b32_e32 v76, 16, v74
	v_and_b32_e32 v77, 0xffff0000, v74
	v_pk_fma_f32 v[222:223], v[42:43], v[60:61], v[62:63]
	v_pk_fma_f32 v[220:221], v[40:41], v[56:57], v[58:59]
	v_lshlrev_b32_e32 v82, 16, v78
	v_and_b32_e32 v83, 0xffff0000, v78
	v_lshlrev_b32_e32 v74, 16, v75
	v_and_b32_e32 v75, 0xffff0000, v75
	v_lshlrev_b32_e32 v78, 16, v79
	v_and_b32_e32 v79, 0xffff0000, v79
	s_nop 1
	v_pk_fma_f32 v[226:227], v[38:39], v[68:69], v[70:71]
	v_pk_fma_f32 v[224:225], v[36:37], v[64:65], v[66:67]
	v_add_u32_e32 v64, 0xa0, v140
	v_ashrrev_i32_e32 v65, 31, v64
	s_nop 0
	v_pk_fma_f32 v[230:231], v[84:85], v[74:75], v[78:79]
	v_pk_fma_f32 v[228:229], v[72:73], v[76:77], v[82:83]
	s_nop 1
	v_permlane16_swap_b32_e32 v216, v220
	v_permlane16_swap_b32_e32 v217, v221
	v_permlane16_swap_b32_e32 v218, v222
	v_permlane16_swap_b32_e32 v219, v223
	v_permlane16_swap_b32_e32 v224, v228
	v_permlane16_swap_b32_e32 v225, v229
	v_permlane16_swap_b32_e32 v226, v230
	v_permlane16_swap_b32_e32 v227, v231
	v_permlane32_swap_b32_e32 v216, v224
	v_permlane32_swap_b32_e32 v217, v225
	v_permlane32_swap_b32_e32 v218, v226
	v_permlane32_swap_b32_e32 v219, v227
	v_permlane32_swap_b32_e32 v220, v228
	v_permlane32_swap_b32_e32 v221, v229
	v_permlane32_swap_b32_e32 v222, v230
	v_permlane32_swap_b32_e32 v223, v231
	v_lshl_add_u64 v[234:235], v[80:81], 0, v[232:233]
	global_store_dwordx4 v[234:235], v[216:219], off
	global_store_dwordx4 v[234:235], v[220:223], off offset:64
	global_store_dwordx4 v[234:235], v[224:227], off offset:128
	global_store_dwordx4 v[234:235], v[228:231], off offset:192
	s_nop 1
	v_lshlrev_b64 v[32:33], 6, v[64:65]
	v_lshl_add_u64 v[48:49], s[6:7], 0, v[32:33]
	global_load_dwordx4 v[32:35], v[48:49], off
	global_load_dwordx4 v[36:39], v[48:49], off offset:16
	global_load_dwordx4 v[40:43], v[48:49], off offset:32
	global_load_dwordx4 v[44:47], v[48:49], off offset:48
	v_lshlrev_b64 v[48:49], 11, v[64:65]
	v_lshl_add_u64 v[50:51], s[8:9], 0, v[48:49]
	v_lshl_add_u64 v[66:67], v[50:51], 0, v[138:139]
	v_lshl_add_u64 v[52:53], s[0:1], 0, v[48:49]
	global_load_dwordx4 v[48:51], v[66:67], off
	v_lshl_add_u64 v[68:69], v[52:53], 0, v[138:139]
	global_load_dwordx4 v[52:55], v[68:69], off
	global_load_dwordx4 v[56:59], v[66:67], off offset:16
	global_load_dwordx4 v[60:63], v[68:69], off offset:16
	s_waitcnt vmcnt(7)
	v_mov_b32_e32 v66, v33
	v_mov_b32_e32 v67, v34
	v_mov_b32_e32 v33, v35
	s_waitcnt vmcnt(6)
	v_mov_b32_e32 v34, v37
	v_mov_b32_e32 v35, v38
	v_mov_b32_e32 v37, v39
	v_pk_add_f32 v[32:33], v[66:67], v[32:33]
	v_pk_add_f32 v[34:35], v[34:35], v[36:37]
	v_pk_add_f32 v[32:33], v[32:33], v[32:33] op_sel:[0,1] op_sel_hi:[1,0]
	v_pk_add_f32 v[34:35], v[34:35], v[34:35] op_sel:[0,1] op_sel_hi:[1,0]
	s_waitcnt vmcnt(5)
	v_add_f32_e32 v36, v40, v41
	v_add_f32_e32 v38, v42, v43
	s_waitcnt vmcnt(4)
	v_mov_b32_e32 v33, v44
	v_mov_b32_e32 v35, v45
	v_mov_b32_e32 v37, v46
	v_mov_b32_e32 v39, v47
	v_pk_add_f32 v[32:33], v[32:33], v[34:35]
	v_pk_add_f32 v[34:35], v[36:37], v[38:39]
	s_waitcnt vmcnt(3)
	v_lshlrev_b32_e32 v36, 16, v49
	v_pk_add_f32 v[32:33], v[32:33], v[34:35]
	v_and_b32_e32 v37, 0xffff0000, v49
	v_add_f32_e32 v32, v32, v33
	v_fmamk_f32 v32, v32, 0x3a800000, v150
	v_mul_f32_e32 v33, 0x4b800000, v32
	v_cmp_gt_f32_e32 vcc, s51, v32
	s_waitcnt vmcnt(1)
	v_and_b32_e32 v49, 0xffff0000, v56
	v_lshlrev_b32_e32 v34, 16, v52
	v_cndmask_b32_e32 v32, v32, v33, vcc
	v_rsq_f32_e32 v32, v32
	v_and_b32_e32 v35, 0xffff0000, v52
	v_lshlrev_b32_e32 v38, 16, v53
	v_and_b32_e32 v39, 0xffff0000, v53
	v_mul_f32_e32 v33, 0x45800000, v32
	v_cndmask_b32_e32 v32, v32, v33, vcc
	v_mul_f32_e32 v67, 0xbfb8aa3b, v32
	v_mul_f32_e32 v16, v16, v67
	v_exp_f32_e32 v16, v16
	v_mul_f32_e32 v17, v17, v67
	v_exp_f32_e32 v17, v17
	v_mul_f32_e32 v28, v28, v67
	v_add_f32_e32 v16, 1.0, v16
	v_mul_f32_e32 v29, v29, v67
	v_lshlrev_b32_e32 v32, 16, v48
	v_and_b32_e32 v33, 0xffff0000, v48
	v_mul_f32_e32 v30, v30, v67
	v_mul_f32_e32 v31, v31, v67
	v_lshlrev_b32_e32 v48, 16, v56
	v_rcp_f32_e32 v56, v16
	v_add_f32_e32 v16, 1.0, v17
	v_exp_f32_e32 v28, v28
	v_exp_f32_e32 v29, v29
	v_exp_f32_e32 v30, v30
	v_exp_f32_e32 v31, v31
	v_mul_f32_e32 v24, v24, v67
	v_mul_f32_e32 v25, v25, v67
	v_mul_f32_e32 v26, v26, v67
	v_mul_f32_e32 v27, v27, v67
	v_lshlrev_b32_e32 v52, 16, v57
	v_and_b32_e32 v53, 0xffff0000, v57
	v_rcp_f32_e32 v57, v16
	v_mul_f32_e32 v16, v18, v67
	v_exp_f32_e32 v24, v24
	v_exp_f32_e32 v25, v25
	v_exp_f32_e32 v26, v26
	v_exp_f32_e32 v27, v27
	v_mul_f32_e32 v20, v20, v67
	v_mul_f32_e32 v21, v21, v67
	v_mul_f32_e32 v22, v22, v67
	v_mul_f32_e32 v23, v23, v67
	v_exp_f32_e32 v16, v16
	v_mul_f32_e32 v17, v19, v67
	v_exp_f32_e32 v20, v20
	v_exp_f32_e32 v21, v21
	v_exp_f32_e32 v22, v22
	v_exp_f32_e32 v23, v23
	v_exp_f32_e32 v17, v17
	v_add_f32_e32 v28, 1.0, v28
	v_add_f32_e32 v29, 1.0, v29
	v_add_f32_e32 v30, 1.0, v30
	v_add_f32_e32 v31, 1.0, v31
	v_rcp_f32_e32 v28, v28
	v_rcp_f32_e32 v29, v29
	v_rcp_f32_e32 v30, v30
	v_rcp_f32_e32 v31, v31
	v_add_f32_e32 v24, 1.0, v24
	v_add_f32_e32 v25, 1.0, v25
	v_add_f32_e32 v26, 1.0, v26
	v_add_f32_e32 v27, 1.0, v27
	v_add_f32_e32 v16, 1.0, v16
	v_rcp_f32_e32 v24, v24
	v_rcp_f32_e32 v25, v25
	v_rcp_f32_e32 v26, v26
	v_rcp_f32_e32 v27, v27
	v_add_f32_e32 v20, 1.0, v20
	v_add_f32_e32 v21, 1.0, v21
	v_add_f32_e32 v22, 1.0, v22
	v_add_f32_e32 v23, 1.0, v23
	v_rcp_f32_e32 v68, v16
	v_add_f32_e32 v16, 1.0, v17
	v_rcp_f32_e32 v20, v20
	v_rcp_f32_e32 v21, v21
	v_rcp_f32_e32 v22, v22
	v_rcp_f32_e32 v23, v23
	v_rcp_f32_e32 v69, v16
	v_lshlrev_b64 v[16:17], 12, v[64:65]
	v_lshl_add_u64 v[16:17], s[84:85], 0, v[16:17]
	v_lshlrev_b32_e32 v40, 16, v50
	v_and_b32_e32 v41, 0xffff0000, v50
	v_lshlrev_b32_e32 v42, 16, v54
	v_and_b32_e32 v43, 0xffff0000, v54
	v_lshlrev_b32_e32 v44, 16, v51
	v_and_b32_e32 v45, 0xffff0000, v51
	v_lshlrev_b32_e32 v46, 16, v55
	v_and_b32_e32 v47, 0xffff0000, v55
	v_lshl_add_u64 v[64:65], v[16:17], 0, v[112:113]
	v_pk_fma_f32 v[218:219], v[30:31], v[36:37], v[38:39]
	v_pk_fma_f32 v[216:217], v[28:29], v[32:33], v[34:35]
	s_waitcnt vmcnt(0)
	v_lshlrev_b32_e32 v50, 16, v60
	v_and_b32_e32 v51, 0xffff0000, v60
	v_lshlrev_b32_e32 v54, 16, v61
	v_and_b32_e32 v55, 0xffff0000, v61
	v_lshlrev_b32_e32 v60, 16, v58
	v_and_b32_e32 v61, 0xffff0000, v58
	v_pk_fma_f32 v[222:223], v[26:27], v[44:45], v[46:47]
	v_pk_fma_f32 v[220:221], v[24:25], v[40:41], v[42:43]
	v_lshlrev_b32_e32 v66, 16, v62
	v_and_b32_e32 v67, 0xffff0000, v62
	v_lshlrev_b32_e32 v58, 16, v59
	v_and_b32_e32 v59, 0xffff0000, v59
	v_lshlrev_b32_e32 v62, 16, v63
	v_and_b32_e32 v63, 0xffff0000, v63
	s_nop 1
	v_pk_fma_f32 v[226:227], v[22:23], v[52:53], v[54:55]
	v_pk_fma_f32 v[224:225], v[20:21], v[48:49], v[50:51]
	v_add_u32_e32 v48, 0xb0, v140
	v_ashrrev_i32_e32 v49, 31, v48
	s_nop 0
	v_pk_fma_f32 v[230:231], v[68:69], v[58:59], v[62:63]
	v_pk_fma_f32 v[228:229], v[56:57], v[60:61], v[66:67]
	s_nop 1
	v_permlane16_swap_b32_e32 v216, v220
	v_permlane16_swap_b32_e32 v217, v221
	v_permlane16_swap_b32_e32 v218, v222
	v_permlane16_swap_b32_e32 v219, v223
	v_permlane16_swap_b32_e32 v224, v228
	v_permlane16_swap_b32_e32 v225, v229
	v_permlane16_swap_b32_e32 v226, v230
	v_permlane16_swap_b32_e32 v227, v231
	v_permlane32_swap_b32_e32 v216, v224
	v_permlane32_swap_b32_e32 v217, v225
	v_permlane32_swap_b32_e32 v218, v226
	v_permlane32_swap_b32_e32 v219, v227
	v_permlane32_swap_b32_e32 v220, v228
	v_permlane32_swap_b32_e32 v221, v229
	v_permlane32_swap_b32_e32 v222, v230
	v_permlane32_swap_b32_e32 v223, v231
	v_lshl_add_u64 v[234:235], v[64:65], 0, v[232:233]
	global_store_dwordx4 v[234:235], v[216:219], off
	global_store_dwordx4 v[234:235], v[220:223], off offset:64
	global_store_dwordx4 v[234:235], v[224:227], off offset:128
	global_store_dwordx4 v[234:235], v[228:231], off offset:192
	s_nop 1
	v_lshlrev_b64 v[16:17], 6, v[48:49]
	v_lshl_add_u64 v[32:33], s[6:7], 0, v[16:17]
	global_load_dwordx4 v[16:19], v[32:33], off
	global_load_dwordx4 v[20:23], v[32:33], off offset:16
	global_load_dwordx4 v[24:27], v[32:33], off offset:32
	global_load_dwordx4 v[28:31], v[32:33], off offset:48
	v_lshlrev_b64 v[32:33], 11, v[48:49]
	v_lshl_add_u64 v[34:35], s[8:9], 0, v[32:33]
	v_lshl_add_u64 v[50:51], v[34:35], 0, v[138:139]
	v_lshl_add_u64 v[36:37], s[0:1], 0, v[32:33]
	global_load_dwordx4 v[32:35], v[50:51], off
	v_lshl_add_u64 v[52:53], v[36:37], 0, v[138:139]
	global_load_dwordx4 v[36:39], v[52:53], off
	global_load_dwordx4 v[40:43], v[50:51], off offset:16
	global_load_dwordx4 v[44:47], v[52:53], off offset:16
	s_waitcnt vmcnt(7)
	v_mov_b32_e32 v50, v17
	v_mov_b32_e32 v51, v18
	v_mov_b32_e32 v17, v19
	s_waitcnt vmcnt(6)
	v_mov_b32_e32 v18, v21
	v_mov_b32_e32 v19, v22
	v_mov_b32_e32 v21, v23
	v_pk_add_f32 v[16:17], v[50:51], v[16:17]
	v_pk_add_f32 v[18:19], v[18:19], v[20:21]
	v_pk_add_f32 v[16:17], v[16:17], v[16:17] op_sel:[0,1] op_sel_hi:[1,0]
	v_pk_add_f32 v[18:19], v[18:19], v[18:19] op_sel:[0,1] op_sel_hi:[1,0]
	s_waitcnt vmcnt(5)
	v_add_f32_e32 v20, v24, v25
	v_add_f32_e32 v22, v26, v27
	s_waitcnt vmcnt(4)
	v_mov_b32_e32 v17, v28
	v_mov_b32_e32 v19, v29
	v_mov_b32_e32 v21, v30
	v_mov_b32_e32 v23, v31
	v_pk_add_f32 v[16:17], v[16:17], v[18:19]
	v_pk_add_f32 v[18:19], v[20:21], v[22:23]
	s_waitcnt vmcnt(3)
	v_lshlrev_b32_e32 v20, 16, v33
	v_pk_add_f32 v[16:17], v[16:17], v[18:19]
	v_and_b32_e32 v21, 0xffff0000, v33
	v_add_f32_e32 v16, v16, v17
	v_fmamk_f32 v16, v16, 0x3a800000, v150
	v_mul_f32_e32 v17, 0x4b800000, v16
	v_cmp_gt_f32_e32 vcc, s51, v16
	s_waitcnt vmcnt(1)
	v_and_b32_e32 v33, 0xffff0000, v40
	v_lshlrev_b32_e32 v18, 16, v36
	v_cndmask_b32_e32 v16, v16, v17, vcc
	v_rsq_f32_e32 v16, v16
	v_and_b32_e32 v19, 0xffff0000, v36
	v_lshlrev_b32_e32 v22, 16, v37
	v_and_b32_e32 v23, 0xffff0000, v37
	v_mul_f32_e32 v17, 0x45800000, v16
	v_cndmask_b32_e32 v16, v16, v17, vcc
	v_mul_f32_e32 v51, 0xbfb8aa3b, v16
	v_mul_f32_e32 v0, v0, v51
	v_exp_f32_e32 v0, v0
	v_mul_f32_e32 v1, v1, v51
	v_exp_f32_e32 v1, v1
	v_mul_f32_e32 v12, v12, v51
	v_add_f32_e32 v0, 1.0, v0
	v_mul_f32_e32 v13, v13, v51
	v_lshlrev_b32_e32 v16, 16, v32
	v_and_b32_e32 v17, 0xffff0000, v32
	v_mul_f32_e32 v14, v14, v51
	v_mul_f32_e32 v15, v15, v51
	v_lshlrev_b32_e32 v32, 16, v40
	v_rcp_f32_e32 v40, v0
	v_add_f32_e32 v0, 1.0, v1
	v_exp_f32_e32 v12, v12
	v_exp_f32_e32 v13, v13
	v_exp_f32_e32 v14, v14
	v_exp_f32_e32 v15, v15
	v_mul_f32_e32 v8, v8, v51
	v_mul_f32_e32 v9, v9, v51
	v_mul_f32_e32 v10, v10, v51
	v_mul_f32_e32 v11, v11, v51
	v_lshlrev_b32_e32 v36, 16, v41
	v_and_b32_e32 v37, 0xffff0000, v41
	v_rcp_f32_e32 v41, v0
	v_mul_f32_e32 v0, v2, v51
	v_exp_f32_e32 v8, v8
	v_exp_f32_e32 v9, v9
	v_exp_f32_e32 v10, v10
	v_exp_f32_e32 v11, v11
	v_mul_f32_e32 v4, v4, v51
	v_mul_f32_e32 v5, v5, v51
	v_mul_f32_e32 v6, v6, v51
	v_mul_f32_e32 v7, v7, v51
	v_exp_f32_e32 v0, v0
	v_mul_f32_e32 v1, v3, v51
	v_exp_f32_e32 v4, v4
	v_exp_f32_e32 v5, v5
	v_exp_f32_e32 v6, v6
	v_exp_f32_e32 v7, v7
	v_exp_f32_e32 v1, v1
	v_add_f32_e32 v12, 1.0, v12
	v_add_f32_e32 v13, 1.0, v13
	v_add_f32_e32 v14, 1.0, v14
	v_add_f32_e32 v15, 1.0, v15
	v_rcp_f32_e32 v12, v12
	v_rcp_f32_e32 v13, v13
	v_rcp_f32_e32 v14, v14
	v_rcp_f32_e32 v15, v15
	v_add_f32_e32 v8, 1.0, v8
	v_add_f32_e32 v9, 1.0, v9
	v_add_f32_e32 v10, 1.0, v10
	v_add_f32_e32 v11, 1.0, v11
	v_add_f32_e32 v0, 1.0, v0
	v_rcp_f32_e32 v8, v8
	v_rcp_f32_e32 v9, v9
	v_rcp_f32_e32 v10, v10
	v_rcp_f32_e32 v11, v11
	v_add_f32_e32 v4, 1.0, v4
	v_add_f32_e32 v5, 1.0, v5
	v_add_f32_e32 v6, 1.0, v6
	v_add_f32_e32 v7, 1.0, v7
	v_rcp_f32_e32 v52, v0
	v_add_f32_e32 v0, 1.0, v1
	v_rcp_f32_e32 v4, v4
	v_rcp_f32_e32 v5, v5
	v_rcp_f32_e32 v6, v6
	v_rcp_f32_e32 v7, v7
	v_rcp_f32_e32 v53, v0
	v_lshlrev_b64 v[0:1], 12, v[48:49]
	v_lshl_add_u64 v[0:1], s[84:85], 0, v[0:1]
	v_lshlrev_b32_e32 v24, 16, v34
	v_and_b32_e32 v25, 0xffff0000, v34
	v_lshlrev_b32_e32 v26, 16, v38
	v_and_b32_e32 v27, 0xffff0000, v38
	v_lshlrev_b32_e32 v28, 16, v35
	v_and_b32_e32 v29, 0xffff0000, v35
	v_lshlrev_b32_e32 v30, 16, v39
	v_and_b32_e32 v31, 0xffff0000, v39
	v_lshl_add_u64 v[48:49], v[0:1], 0, v[112:113]
	v_pk_fma_f32 v[218:219], v[14:15], v[20:21], v[22:23]
	v_pk_fma_f32 v[216:217], v[12:13], v[16:17], v[18:19]
	s_waitcnt vmcnt(0)
	v_lshlrev_b32_e32 v34, 16, v44
	v_and_b32_e32 v35, 0xffff0000, v44
	v_lshlrev_b32_e32 v38, 16, v45
	v_and_b32_e32 v39, 0xffff0000, v45
	v_lshlrev_b32_e32 v44, 16, v42
	v_and_b32_e32 v45, 0xffff0000, v42
	v_pk_fma_f32 v[222:223], v[10:11], v[28:29], v[30:31]
	v_pk_fma_f32 v[220:221], v[8:9], v[24:25], v[26:27]
	v_lshlrev_b32_e32 v50, 16, v46
	v_and_b32_e32 v51, 0xffff0000, v46
	v_lshlrev_b32_e32 v42, 16, v43
	v_and_b32_e32 v43, 0xffff0000, v43
	v_lshlrev_b32_e32 v46, 16, v47
	v_and_b32_e32 v47, 0xffff0000, v47
	s_nop 1
	v_pk_fma_f32 v[226:227], v[6:7], v[36:37], v[38:39]
	v_pk_fma_f32 v[224:225], v[4:5], v[32:33], v[34:35]
	s_nop 1
	v_pk_fma_f32 v[230:231], v[52:53], v[42:43], v[46:47]
	v_pk_fma_f32 v[228:229], v[40:41], v[44:45], v[50:51]
	s_nop 1
	v_permlane16_swap_b32_e32 v216, v220
	v_permlane16_swap_b32_e32 v217, v221
	v_permlane16_swap_b32_e32 v218, v222
	v_permlane16_swap_b32_e32 v219, v223
	v_permlane16_swap_b32_e32 v224, v228
	v_permlane16_swap_b32_e32 v225, v229
	v_permlane16_swap_b32_e32 v226, v230
	v_permlane16_swap_b32_e32 v227, v231
	v_permlane32_swap_b32_e32 v216, v224
	v_permlane32_swap_b32_e32 v217, v225
	v_permlane32_swap_b32_e32 v218, v226
	v_permlane32_swap_b32_e32 v219, v227
	v_permlane32_swap_b32_e32 v220, v228
	v_permlane32_swap_b32_e32 v221, v229
	v_permlane32_swap_b32_e32 v222, v230
	v_permlane32_swap_b32_e32 v223, v231
	v_lshl_add_u64 v[234:235], v[48:49], 0, v[232:233]
	global_store_dwordx4 v[234:235], v[216:219], off
	global_store_dwordx4 v[234:235], v[220:223], off offset:64
	global_store_dwordx4 v[234:235], v[224:227], off offset:128
	global_store_dwordx4 v[234:235], v[228:231], off offset:192
	s_cbranch_scc1 .LBB0_1643
	s_andn2_b64 vcc, exec, s[4:5]
	s_cbranch_vccnz .LBB0_1642
	s_barrier
	s_branch .LBB0_1642
